# P8 epilogue: store address of blocks 1..7 derived from block 0 by adding the constant row stride instead of recomputing the 64-bit mad per block
# speedup vs baseline: 1.0317x; 1.0046x over previous
; #define PG8_LAS __attribute__((address_space(3)))
; __device__ __forceinline__ u32x4 pack8(f32x4 v0, f32x4 v1) { u32x4 w; w.x = cvt_pk_bf16(v0[0], v0[1]); w.y = cvt_pk_bf16(v0[2], v0[3]); w.z = cvt_pk_bf16(v1[0], v1[1]); w.w = cvt_pk_bf16(v1[2], v1[3]); return w; }
;     __device__ __forceinline__ void operator()(Acc& acc, const Unit& u, int wr, int wc, int fr, int fq, PG8_LAS unsigned char* xl) const {
;         const PG8_LAS float* S = rs_table(SS, u.r0, xl);
; #pragma unroll
;         for (int ai = 0; ai < 2; ++ai)
; #pragma unroll
;             for (int m = 0; m < 4; ++m) { const int rl = ai * HALF + wr * 64 + m * 16 + fr; const int row = u.r0 + rl; const float s = S[rl], cs = -LOG2E * s, s2 = s * s;
;                 f32x4 o[2];
; #pragma unroll
;                 for (int n = 0; n < 2; ++n) { const f32x4 g = acc[ai][0][m][n], gu = acc[ai][0][m][n] * acc[ai][1][m][n]; f32x4 r;
; #pragma unroll
;                     for (int e = 0; e < 4; ++e) r[e] = gu[e] * (s2 * __builtin_amdgcn_rcpf(1.f + __builtin_amdgcn_exp2f(cs * g[e])));
;                     o[n] = r; }
;                 *(u32x4*)(H + (size_t)row * ldc + (u.c0 >> 1) + wc * 32 + 8 * fq) = pack8(o[0], o[1]); }
.Lrs8_skip:
	ds_read_b32 v184, v148
	ds_read_b32 v185, v150
	ds_read_b32 v186, v152
	ds_read_b32 v187, v155
	ds_read_b32 v188, v157
	ds_read_b32 v189, v159
	ds_read_b32 v190, v161
	ds_read_b32 v191, v163
	s_ashr_i32 s2, s33, 1
	s_ashr_i32 s3, s2, 31
	s_lshl_b64 s[2:3], s[2:3], 1
	v_mov_b64_e32 v[170:171], s[12:13]
	v_mov_b32_e32 v180, 1.0
	v_pk_mul_f32 v[120:121], v[124:125], v[120:121]
	v_pk_mul_f32 v[122:123], v[126:127], v[122:123]
	v_pk_mul_f32 v[112:113], v[116:117], v[112:113]
	v_pk_mul_f32 v[114:115], v[118:119], v[114:115]
	s_waitcnt lgkmcnt(0)
	v_mul_f32_e32 v174, 0xbfb8aa3b, v184
	v_mul_f32_e32 v176, v184, v184
	v_pk_mul_f32 v[124:125], v[124:125], v[174:175] op_sel_hi:[1,0]
	v_pk_mul_f32 v[126:127], v[126:127], v[174:175] op_sel_hi:[1,0]
	v_pk_mul_f32 v[116:117], v[116:117], v[174:175] op_sel_hi:[1,0]
	v_pk_mul_f32 v[118:119], v[118:119], v[174:175] op_sel_hi:[1,0]
	v_exp_f32_e32 v124, v124
	v_exp_f32_e32 v125, v125
	v_exp_f32_e32 v126, v126
	v_exp_f32_e32 v127, v127
	v_exp_f32_e32 v116, v116
	v_exp_f32_e32 v117, v117
	v_exp_f32_e32 v118, v118
	v_exp_f32_e32 v119, v119
	v_pk_add_f32 v[124:125], v[124:125], v[180:181] op_sel_hi:[1,0]
	v_pk_add_f32 v[126:127], v[126:127], v[180:181] op_sel_hi:[1,0]
	v_pk_add_f32 v[116:117], v[116:117], v[180:181] op_sel_hi:[1,0]
	v_pk_add_f32 v[118:119], v[118:119], v[180:181] op_sel_hi:[1,0]
	v_add_u32_e32 v172, s60, v146
	v_rcp_f32_e32 v124, v124
	v_rcp_f32_e32 v125, v125
	v_rcp_f32_e32 v126, v126
	v_rcp_f32_e32 v127, v127
	v_mad_i64_i32 v[172:173], s[30:31], v172, s64, v[170:171]
	v_rcp_f32_e32 v116, v116
	v_rcp_f32_e32 v117, v117
	v_rcp_f32_e32 v118, v118
	v_rcp_f32_e32 v119, v119
	v_lshl_add_u64 v[172:173], v[172:173], 0, s[2:3]
	v_lshl_add_u64 v[172:173], v[172:173], 0, s[8:9]
	v_lshl_add_u64 v[172:173], v[172:173], 0, v[136:137]
	v_pk_mul_f32 v[124:125], v[124:125], v[176:177] op_sel_hi:[1,0]
	v_pk_mul_f32 v[126:127], v[126:127], v[176:177] op_sel_hi:[1,0]
	v_pk_mul_f32 v[116:117], v[116:117], v[176:177] op_sel_hi:[1,0]
	v_pk_mul_f32 v[118:119], v[118:119], v[176:177] op_sel_hi:[1,0]
	v_pk_mul_f32 v[120:121], v[120:121], v[124:125]
	v_pk_mul_f32 v[122:123], v[122:123], v[126:127]
	v_pk_mul_f32 v[112:113], v[112:113], v[116:117]
	v_pk_mul_f32 v[114:115], v[114:115], v[118:119]
	v_cvt_pk_bf16_f32 v124, v120, v121
	v_cvt_pk_bf16_f32 v125, v122, v123
	v_cvt_pk_bf16_f32 v126, v112, v113
	v_cvt_pk_bf16_f32 v127, v114, v115
	flat_store_dwordx4 v[172:173], v[124:127]
	v_pk_mul_f32 v[104:105], v[108:109], v[104:105]
	v_pk_mul_f32 v[106:107], v[110:111], v[106:107]
	v_pk_mul_f32 v[96:97], v[100:101], v[96:97]
	v_pk_mul_f32 v[98:99], v[102:103], v[98:99]
	v_mul_f32_e32 v174, 0xbfb8aa3b, v185
	v_mul_f32_e32 v176, v185, v185
	v_pk_mul_f32 v[108:109], v[108:109], v[174:175] op_sel_hi:[1,0]
	v_pk_mul_f32 v[110:111], v[110:111], v[174:175] op_sel_hi:[1,0]
	v_pk_mul_f32 v[100:101], v[100:101], v[174:175] op_sel_hi:[1,0]
	v_pk_mul_f32 v[102:103], v[102:103], v[174:175] op_sel_hi:[1,0]
	v_exp_f32_e32 v108, v108
	v_exp_f32_e32 v109, v109
	v_exp_f32_e32 v110, v110
	v_exp_f32_e32 v111, v111
	v_exp_f32_e32 v100, v100
	v_exp_f32_e32 v101, v101
	v_exp_f32_e32 v102, v102
	v_exp_f32_e32 v103, v103
	v_pk_add_f32 v[108:109], v[108:109], v[180:181] op_sel_hi:[1,0]
	v_pk_add_f32 v[110:111], v[110:111], v[180:181] op_sel_hi:[1,0]
	v_pk_add_f32 v[100:101], v[100:101], v[180:181] op_sel_hi:[1,0]
	v_pk_add_f32 v[102:103], v[102:103], v[180:181] op_sel_hi:[1,0]
	v_add_co_u32_e32 v172, vcc, 0x16000, v172
	v_rcp_f32_e32 v108, v108
	v_rcp_f32_e32 v109, v109
	v_rcp_f32_e32 v110, v110
	v_rcp_f32_e32 v111, v111
	v_addc_co_u32_e32 v173, vcc, 0, v173, vcc
	v_rcp_f32_e32 v100, v100
	v_rcp_f32_e32 v101, v101
	v_rcp_f32_e32 v102, v102
	v_rcp_f32_e32 v103, v103
	v_pk_mul_f32 v[108:109], v[108:109], v[176:177] op_sel_hi:[1,0]
	v_pk_mul_f32 v[110:111], v[110:111], v[176:177] op_sel_hi:[1,0]
	v_pk_mul_f32 v[100:101], v[100:101], v[176:177] op_sel_hi:[1,0]
	v_pk_mul_f32 v[102:103], v[102:103], v[176:177] op_sel_hi:[1,0]
	v_pk_mul_f32 v[104:105], v[104:105], v[108:109]
	v_pk_mul_f32 v[106:107], v[106:107], v[110:111]
	v_pk_mul_f32 v[96:97], v[96:97], v[100:101]
	v_pk_mul_f32 v[98:99], v[98:99], v[102:103]
	v_cvt_pk_bf16_f32 v108, v104, v105
	v_cvt_pk_bf16_f32 v109, v106, v107
	v_cvt_pk_bf16_f32 v110, v96, v97
	v_cvt_pk_bf16_f32 v111, v98, v99
	flat_store_dwordx4 v[172:173], v[108:111]
	v_pk_mul_f32 v[88:89], v[92:93], v[88:89]
	v_pk_mul_f32 v[90:91], v[94:95], v[90:91]
	v_pk_mul_f32 v[80:81], v[84:85], v[80:81]
	v_pk_mul_f32 v[82:83], v[86:87], v[82:83]
	v_mul_f32_e32 v174, 0xbfb8aa3b, v186
	v_mul_f32_e32 v176, v186, v186
	v_pk_mul_f32 v[92:93], v[92:93], v[174:175] op_sel_hi:[1,0]
	v_pk_mul_f32 v[94:95], v[94:95], v[174:175] op_sel_hi:[1,0]
	v_pk_mul_f32 v[84:85], v[84:85], v[174:175] op_sel_hi:[1,0]
	v_pk_mul_f32 v[86:87], v[86:87], v[174:175] op_sel_hi:[1,0]
	v_exp_f32_e32 v92, v92
	v_exp_f32_e32 v93, v93
	v_exp_f32_e32 v94, v94
	v_exp_f32_e32 v95, v95
	v_exp_f32_e32 v84, v84
	v_exp_f32_e32 v85, v85
	v_exp_f32_e32 v86, v86
	v_exp_f32_e32 v87, v87
	v_pk_add_f32 v[92:93], v[92:93], v[180:181] op_sel_hi:[1,0]
	v_pk_add_f32 v[94:95], v[94:95], v[180:181] op_sel_hi:[1,0]
	v_pk_add_f32 v[84:85], v[84:85], v[180:181] op_sel_hi:[1,0]
	v_pk_add_f32 v[86:87], v[86:87], v[180:181] op_sel_hi:[1,0]
	v_add_co_u32_e32 v172, vcc, 0x16000, v172
	v_rcp_f32_e32 v92, v92
	v_rcp_f32_e32 v93, v93
	v_rcp_f32_e32 v94, v94
	v_rcp_f32_e32 v95, v95
	v_addc_co_u32_e32 v173, vcc, 0, v173, vcc
	v_rcp_f32_e32 v84, v84
	v_rcp_f32_e32 v85, v85
	v_rcp_f32_e32 v86, v86
	v_rcp_f32_e32 v87, v87
	v_pk_mul_f32 v[92:93], v[92:93], v[176:177] op_sel_hi:[1,0]
; __device__ __forceinline__ u32x4 pack8(f32x4 v0, f32x4 v1) { u32x4 w; w.x = cvt_pk_bf16(v0[0], v0[1]); w.y = cvt_pk_bf16(v0[2], v0[3]); w.z = cvt_pk_bf16(v1[0], v1[1]); w.w = cvt_pk_bf16(v1[2], v1[3]); return w; }
;     __device__ __forceinline__ void operator()(Acc& acc, const Unit& u, int wr, int wc, int fr, int fq, PG8_LAS unsigned char* xl) const {
;     ...
;         for (int ai = 0; ai < 2; ++ai)
; #pragma unroll
;             for (int m = 0; m < 4; ++m) { const int rl = ai * HALF + wr * 64 + m * 16 + fr; const int row = u.r0 + rl; const float s = S[rl], cs = -LOG2E * s, s2 = s * s;
;                 f32x4 o[2];
; #pragma unroll
;                 for (int n = 0; n < 2; ++n) { const f32x4 g = acc[ai][0][m][n], gu = acc[ai][0][m][n] * acc[ai][1][m][n]; f32x4 r;
; #pragma unroll
;                     for (int e = 0; e < 4; ++e) r[e] = gu[e] * (s2 * __builtin_amdgcn_rcpf(1.f + __builtin_amdgcn_exp2f(cs * g[e])));
;                     o[n] = r; }
;                 *(u32x4*)(H + (size_t)row * ldc + (u.c0 >> 1) + wc * 32 + 8 * fq) = pack8(o[0], o[1]); }
	v_pk_mul_f32 v[94:95], v[94:95], v[176:177] op_sel_hi:[1,0]
	v_pk_mul_f32 v[84:85], v[84:85], v[176:177] op_sel_hi:[1,0]
	v_pk_mul_f32 v[86:87], v[86:87], v[176:177] op_sel_hi:[1,0]
	v_pk_mul_f32 v[88:89], v[88:89], v[92:93]
	v_pk_mul_f32 v[90:91], v[90:91], v[94:95]
	v_pk_mul_f32 v[80:81], v[80:81], v[84:85]
	v_pk_mul_f32 v[82:83], v[82:83], v[86:87]
	v_cvt_pk_bf16_f32 v92, v88, v89
	v_cvt_pk_bf16_f32 v93, v90, v91
	v_cvt_pk_bf16_f32 v94, v80, v81
	v_cvt_pk_bf16_f32 v95, v82, v83
	flat_store_dwordx4 v[172:173], v[92:95]
	v_pk_mul_f32 v[72:73], v[76:77], v[72:73]
	v_pk_mul_f32 v[74:75], v[78:79], v[74:75]
	v_pk_mul_f32 v[64:65], v[68:69], v[64:65]
	v_pk_mul_f32 v[66:67], v[70:71], v[66:67]
	v_mul_f32_e32 v174, 0xbfb8aa3b, v187
	v_mul_f32_e32 v176, v187, v187
	v_pk_mul_f32 v[76:77], v[76:77], v[174:175] op_sel_hi:[1,0]
	v_pk_mul_f32 v[78:79], v[78:79], v[174:175] op_sel_hi:[1,0]
	v_pk_mul_f32 v[68:69], v[68:69], v[174:175] op_sel_hi:[1,0]
	v_pk_mul_f32 v[70:71], v[70:71], v[174:175] op_sel_hi:[1,0]
	v_exp_f32_e32 v76, v76
	v_exp_f32_e32 v77, v77
	v_exp_f32_e32 v78, v78
	v_exp_f32_e32 v79, v79
	v_exp_f32_e32 v68, v68
	v_exp_f32_e32 v69, v69
	v_exp_f32_e32 v70, v70
	v_exp_f32_e32 v71, v71
	v_pk_add_f32 v[76:77], v[76:77], v[180:181] op_sel_hi:[1,0]
	v_pk_add_f32 v[78:79], v[78:79], v[180:181] op_sel_hi:[1,0]
	v_pk_add_f32 v[68:69], v[68:69], v[180:181] op_sel_hi:[1,0]
	v_pk_add_f32 v[70:71], v[70:71], v[180:181] op_sel_hi:[1,0]
	v_add_co_u32_e32 v172, vcc, 0x16000, v172
	v_rcp_f32_e32 v76, v76
	v_rcp_f32_e32 v77, v77
	v_rcp_f32_e32 v78, v78
	v_rcp_f32_e32 v79, v79
	v_addc_co_u32_e32 v173, vcc, 0, v173, vcc
	v_rcp_f32_e32 v68, v68
	v_rcp_f32_e32 v69, v69
	v_rcp_f32_e32 v70, v70
	v_rcp_f32_e32 v71, v71
	v_pk_mul_f32 v[76:77], v[76:77], v[176:177] op_sel_hi:[1,0]
	v_pk_mul_f32 v[78:79], v[78:79], v[176:177] op_sel_hi:[1,0]
	v_pk_mul_f32 v[68:69], v[68:69], v[176:177] op_sel_hi:[1,0]
	v_pk_mul_f32 v[70:71], v[70:71], v[176:177] op_sel_hi:[1,0]
	v_pk_mul_f32 v[72:73], v[72:73], v[76:77]
	v_pk_mul_f32 v[74:75], v[74:75], v[78:79]
	v_pk_mul_f32 v[64:65], v[64:65], v[68:69]
	v_pk_mul_f32 v[66:67], v[66:67], v[70:71]
	v_cvt_pk_bf16_f32 v76, v72, v73
	v_cvt_pk_bf16_f32 v77, v74, v75
	v_cvt_pk_bf16_f32 v78, v64, v65
	v_cvt_pk_bf16_f32 v79, v66, v67
	flat_store_dwordx4 v[172:173], v[76:79]
	v_pk_mul_f32 v[56:57], v[60:61], v[56:57]
	v_pk_mul_f32 v[58:59], v[62:63], v[58:59]
	v_pk_mul_f32 v[48:49], v[52:53], v[48:49]
	v_pk_mul_f32 v[50:51], v[54:55], v[50:51]
	v_mul_f32_e32 v174, 0xbfb8aa3b, v188
	v_mul_f32_e32 v176, v188, v188
	v_pk_mul_f32 v[60:61], v[60:61], v[174:175] op_sel_hi:[1,0]
	v_pk_mul_f32 v[62:63], v[62:63], v[174:175] op_sel_hi:[1,0]
	v_pk_mul_f32 v[52:53], v[52:53], v[174:175] op_sel_hi:[1,0]
	v_pk_mul_f32 v[54:55], v[54:55], v[174:175] op_sel_hi:[1,0]
	v_exp_f32_e32 v60, v60
	v_exp_f32_e32 v61, v61
	v_exp_f32_e32 v62, v62
	v_exp_f32_e32 v63, v63
	v_exp_f32_e32 v52, v52
	v_exp_f32_e32 v53, v53
	v_exp_f32_e32 v54, v54
	v_exp_f32_e32 v55, v55
	v_pk_add_f32 v[60:61], v[60:61], v[180:181] op_sel_hi:[1,0]
	v_pk_add_f32 v[62:63], v[62:63], v[180:181] op_sel_hi:[1,0]
	v_pk_add_f32 v[52:53], v[52:53], v[180:181] op_sel_hi:[1,0]
	v_pk_add_f32 v[54:55], v[54:55], v[180:181] op_sel_hi:[1,0]
	v_add_co_u32_e32 v172, vcc, 0x6e000, v172
	v_rcp_f32_e32 v60, v60
	v_rcp_f32_e32 v61, v61
	v_rcp_f32_e32 v62, v62
	v_rcp_f32_e32 v63, v63
	v_addc_co_u32_e32 v173, vcc, 0, v173, vcc
	v_rcp_f32_e32 v52, v52
	v_rcp_f32_e32 v53, v53
	v_rcp_f32_e32 v54, v54
	v_rcp_f32_e32 v55, v55
	v_pk_mul_f32 v[60:61], v[60:61], v[176:177] op_sel_hi:[1,0]
	v_pk_mul_f32 v[62:63], v[62:63], v[176:177] op_sel_hi:[1,0]
	v_pk_mul_f32 v[52:53], v[52:53], v[176:177] op_sel_hi:[1,0]
	v_pk_mul_f32 v[54:55], v[54:55], v[176:177] op_sel_hi:[1,0]
	v_pk_mul_f32 v[56:57], v[56:57], v[60:61]
	v_pk_mul_f32 v[58:59], v[58:59], v[62:63]
	v_pk_mul_f32 v[48:49], v[48:49], v[52:53]
	v_pk_mul_f32 v[50:51], v[50:51], v[54:55]
	v_cvt_pk_bf16_f32 v60, v56, v57
	v_cvt_pk_bf16_f32 v61, v58, v59
	v_cvt_pk_bf16_f32 v62, v48, v49
	v_cvt_pk_bf16_f32 v63, v50, v51
	flat_store_dwordx4 v[172:173], v[60:63]
	v_pk_mul_f32 v[40:41], v[44:45], v[40:41]
	v_pk_mul_f32 v[42:43], v[46:47], v[42:43]
	v_pk_mul_f32 v[32:33], v[36:37], v[32:33]
	v_pk_mul_f32 v[34:35], v[38:39], v[34:35]
	v_mul_f32_e32 v174, 0xbfb8aa3b, v189
	v_mul_f32_e32 v176, v189, v189
	v_pk_mul_f32 v[44:45], v[44:45], v[174:175] op_sel_hi:[1,0]
	v_pk_mul_f32 v[46:47], v[46:47], v[174:175] op_sel_hi:[1,0]
	v_pk_mul_f32 v[36:37], v[36:37], v[174:175] op_sel_hi:[1,0]
	v_pk_mul_f32 v[38:39], v[38:39], v[174:175] op_sel_hi:[1,0]
	v_exp_f32_e32 v44, v44
	v_exp_f32_e32 v45, v45
	v_exp_f32_e32 v46, v46
	v_exp_f32_e32 v47, v47
	v_exp_f32_e32 v36, v36
	v_exp_f32_e32 v37, v37
	v_exp_f32_e32 v38, v38
	v_exp_f32_e32 v39, v39
; __device__ __forceinline__ u32x4 pack8(f32x4 v0, f32x4 v1) { u32x4 w; w.x = cvt_pk_bf16(v0[0], v0[1]); w.y = cvt_pk_bf16(v0[2], v0[3]); w.z = cvt_pk_bf16(v1[0], v1[1]); w.w = cvt_pk_bf16(v1[2], v1[3]); return w; }
; #define PG8_BAR __builtin_amdgcn_s_barrier()
;     __device__ __forceinline__ void operator()(Acc& acc, const Unit& u, int wr, int wc, int fr, int fq, PG8_LAS unsigned char* xl) const {
;     ...
;         for (int ai = 0; ai < 2; ++ai)
; #pragma unroll
;             for (int m = 0; m < 4; ++m) { const int rl = ai * HALF + wr * 64 + m * 16 + fr; const int row = u.r0 + rl; const float s = S[rl], cs = -LOG2E * s, s2 = s * s;
;                 f32x4 o[2];
; #pragma unroll
;                 for (int n = 0; n < 2; ++n) { const f32x4 g = acc[ai][0][m][n], gu = acc[ai][0][m][n] * acc[ai][1][m][n]; f32x4 r;
; #pragma unroll
;                     for (int e = 0; e < 4; ++e) r[e] = gu[e] * (s2 * __builtin_amdgcn_rcpf(1.f + __builtin_amdgcn_exp2f(cs * g[e])));
;                     o[n] = r; }
;                 *(u32x4*)(H + (size_t)row * ldc + (u.c0 >> 1) + wc * 32 + 8 * fq) = pack8(o[0], o[1]); }
; template <class Epi, class Sched>
; __device__ __forceinline__ void gemm_phase(PG8_LAS unsigned char* lds, PG8_LAS unsigned char* xl, const Gemm g, const Sched& S, const Epi& E) {
;     ...
;         if (!has_next) break;
; #pragma unroll
;         for (int a = 0; a < 2; ++a)
; #pragma unroll
;             for (int b = 0; b < 2; ++b)
; #pragma unroll
;                 for (int m = 0; m < 4; ++m)
; #pragma unroll
;                     for (int n = 0; n < 2; ++n) acc[a][b][m][n] = (f32x4){0.f, 0.f, 0.f, 0.f};
;         cur = nxt; cA = nA; cB = nB; ++ui;
;         if (wr == 1) PG8_BAR;
	v_pk_add_f32 v[44:45], v[44:45], v[180:181] op_sel_hi:[1,0]
	v_pk_add_f32 v[46:47], v[46:47], v[180:181] op_sel_hi:[1,0]
	v_pk_add_f32 v[36:37], v[36:37], v[180:181] op_sel_hi:[1,0]
	v_pk_add_f32 v[38:39], v[38:39], v[180:181] op_sel_hi:[1,0]
	v_add_co_u32_e32 v172, vcc, 0x16000, v172
	v_rcp_f32_e32 v44, v44
	v_rcp_f32_e32 v45, v45
	v_rcp_f32_e32 v46, v46
	v_rcp_f32_e32 v47, v47
	v_addc_co_u32_e32 v173, vcc, 0, v173, vcc
	v_rcp_f32_e32 v36, v36
	v_rcp_f32_e32 v37, v37
	v_rcp_f32_e32 v38, v38
	v_rcp_f32_e32 v39, v39
	v_pk_mul_f32 v[44:45], v[44:45], v[176:177] op_sel_hi:[1,0]
	v_pk_mul_f32 v[46:47], v[46:47], v[176:177] op_sel_hi:[1,0]
	v_pk_mul_f32 v[36:37], v[36:37], v[176:177] op_sel_hi:[1,0]
	v_pk_mul_f32 v[38:39], v[38:39], v[176:177] op_sel_hi:[1,0]
	v_pk_mul_f32 v[40:41], v[40:41], v[44:45]
	v_pk_mul_f32 v[42:43], v[42:43], v[46:47]
	v_pk_mul_f32 v[32:33], v[32:33], v[36:37]
	v_pk_mul_f32 v[34:35], v[34:35], v[38:39]
	v_cvt_pk_bf16_f32 v44, v40, v41
	v_cvt_pk_bf16_f32 v45, v42, v43
	v_cvt_pk_bf16_f32 v46, v32, v33
	v_cvt_pk_bf16_f32 v47, v34, v35
	flat_store_dwordx4 v[172:173], v[44:47]
	v_pk_mul_f32 v[24:25], v[28:29], v[24:25]
	v_pk_mul_f32 v[26:27], v[30:31], v[26:27]
	v_pk_mul_f32 v[16:17], v[20:21], v[16:17]
	v_pk_mul_f32 v[18:19], v[22:23], v[18:19]
	v_mul_f32_e32 v174, 0xbfb8aa3b, v190
	v_mul_f32_e32 v176, v190, v190
	v_pk_mul_f32 v[28:29], v[28:29], v[174:175] op_sel_hi:[1,0]
	v_pk_mul_f32 v[30:31], v[30:31], v[174:175] op_sel_hi:[1,0]
	v_pk_mul_f32 v[20:21], v[20:21], v[174:175] op_sel_hi:[1,0]
	v_pk_mul_f32 v[22:23], v[22:23], v[174:175] op_sel_hi:[1,0]
	v_exp_f32_e32 v28, v28
	v_exp_f32_e32 v29, v29
	v_exp_f32_e32 v30, v30
	v_exp_f32_e32 v31, v31
	v_exp_f32_e32 v20, v20
	v_exp_f32_e32 v21, v21
	v_exp_f32_e32 v22, v22
	v_exp_f32_e32 v23, v23
	v_pk_add_f32 v[28:29], v[28:29], v[180:181] op_sel_hi:[1,0]
	v_pk_add_f32 v[30:31], v[30:31], v[180:181] op_sel_hi:[1,0]
	v_pk_add_f32 v[20:21], v[20:21], v[180:181] op_sel_hi:[1,0]
	v_pk_add_f32 v[22:23], v[22:23], v[180:181] op_sel_hi:[1,0]
	v_add_co_u32_e32 v172, vcc, 0x16000, v172
	v_rcp_f32_e32 v28, v28
	v_rcp_f32_e32 v29, v29
	v_rcp_f32_e32 v30, v30
	v_rcp_f32_e32 v31, v31
	v_addc_co_u32_e32 v173, vcc, 0, v173, vcc
	v_rcp_f32_e32 v20, v20
	v_rcp_f32_e32 v21, v21
	v_rcp_f32_e32 v22, v22
	v_rcp_f32_e32 v23, v23
	v_pk_mul_f32 v[28:29], v[28:29], v[176:177] op_sel_hi:[1,0]
	v_pk_mul_f32 v[30:31], v[30:31], v[176:177] op_sel_hi:[1,0]
	v_pk_mul_f32 v[20:21], v[20:21], v[176:177] op_sel_hi:[1,0]
	v_pk_mul_f32 v[22:23], v[22:23], v[176:177] op_sel_hi:[1,0]
	v_pk_mul_f32 v[24:25], v[24:25], v[28:29]
	v_pk_mul_f32 v[26:27], v[26:27], v[30:31]
	v_pk_mul_f32 v[16:17], v[16:17], v[20:21]
	v_pk_mul_f32 v[18:19], v[18:19], v[22:23]
	v_cvt_pk_bf16_f32 v28, v24, v25
	v_cvt_pk_bf16_f32 v29, v26, v27
	v_cvt_pk_bf16_f32 v30, v16, v17
	v_cvt_pk_bf16_f32 v31, v18, v19
	flat_store_dwordx4 v[172:173], v[28:31]
	v_pk_mul_f32 v[8:9], v[12:13], v[8:9]
	v_pk_mul_f32 v[10:11], v[14:15], v[10:11]
	v_pk_mul_f32 v[0:1], v[4:5], v[0:1]
	v_pk_mul_f32 v[2:3], v[6:7], v[2:3]
	v_mul_f32_e32 v174, 0xbfb8aa3b, v191
	v_mul_f32_e32 v176, v191, v191
	v_pk_mul_f32 v[12:13], v[12:13], v[174:175] op_sel_hi:[1,0]
	v_pk_mul_f32 v[14:15], v[14:15], v[174:175] op_sel_hi:[1,0]
	v_pk_mul_f32 v[4:5], v[4:5], v[174:175] op_sel_hi:[1,0]
	v_pk_mul_f32 v[6:7], v[6:7], v[174:175] op_sel_hi:[1,0]
	v_exp_f32_e32 v12, v12
	v_exp_f32_e32 v13, v13
	v_exp_f32_e32 v14, v14
	v_exp_f32_e32 v15, v15
	v_exp_f32_e32 v4, v4
	v_exp_f32_e32 v5, v5
	v_exp_f32_e32 v6, v6
	v_exp_f32_e32 v7, v7
	v_pk_add_f32 v[12:13], v[12:13], v[180:181] op_sel_hi:[1,0]
	v_pk_add_f32 v[14:15], v[14:15], v[180:181] op_sel_hi:[1,0]
	v_pk_add_f32 v[4:5], v[4:5], v[180:181] op_sel_hi:[1,0]
	v_pk_add_f32 v[6:7], v[6:7], v[180:181] op_sel_hi:[1,0]
	v_add_co_u32_e32 v172, vcc, 0x16000, v172
	v_rcp_f32_e32 v12, v12
	v_rcp_f32_e32 v13, v13
	v_rcp_f32_e32 v14, v14
	v_rcp_f32_e32 v15, v15
	v_addc_co_u32_e32 v173, vcc, 0, v173, vcc
	v_rcp_f32_e32 v4, v4
	v_rcp_f32_e32 v5, v5
	v_rcp_f32_e32 v6, v6
	v_rcp_f32_e32 v7, v7
	v_pk_mul_f32 v[12:13], v[12:13], v[176:177] op_sel_hi:[1,0]
	v_pk_mul_f32 v[14:15], v[14:15], v[176:177] op_sel_hi:[1,0]
	v_pk_mul_f32 v[4:5], v[4:5], v[176:177] op_sel_hi:[1,0]
	v_pk_mul_f32 v[6:7], v[6:7], v[176:177] op_sel_hi:[1,0]
	v_pk_mul_f32 v[8:9], v[8:9], v[12:13]
	v_pk_mul_f32 v[10:11], v[10:11], v[14:15]
	v_pk_mul_f32 v[0:1], v[0:1], v[4:5]
	v_pk_mul_f32 v[2:3], v[2:3], v[6:7]
	v_cvt_pk_bf16_f32 v12, v8, v9
	v_cvt_pk_bf16_f32 v13, v10, v11
	v_cvt_pk_bf16_f32 v14, v0, v1
	v_cvt_pk_bf16_f32 v15, v2, v3
	flat_store_dwordx4 v[172:173], v[12:15]
	s_andn2_b64 vcc, exec, s[6:7]
	s_mov_b64 s[2:3], -1
	s_cbranch_vccnz .LBB0_821
	s_andn2_b64 vcc, exec, s[10:11]
	s_cbranch_vccnz .LBB0_820
	s_barrier
	s_branch .LBB0_820
